# attention tile loop: second-half V transposed LDS reads also moved into the MFMA-to-VALU wait slot
# speedup vs baseline: 1.0096x; 1.0048x over previous
; #define LAS __attribute__((address_space(3)))
; DI unsigned pk2(float lo, float hi) { f32x2 v = {lo, hi}; bfv2 b = __builtin_convertvector(v, bfv2); return __builtin_bit_cast(unsigned, b); }
; DI f32x16 mfma32(bf16x8 a, bf16x8 b, f32x16 c) { return __builtin_amdgcn_mfma_f32_32x32x16_bf16(a, b, c, 0, 0, 0); }
; DI void attn_unit(const Params& p, int unit, unsigned char* lds) {
;     ...
;   for (int tl = 0; tl < 64; ++tl) {
;     { const int tn_ = tl + 1 < 64 ? tl + 1 : 63; AT_LOAD(tn_); }
;     asm volatile("" ::: "memory"); __builtin_amdgcn_sched_barrier(0);
;     const bf16_t* k_ = Ks + (tl & 1) * 64 * 72; const bf16_t* v_ = Vs + (tl & 1) * 64 * 72;
; #pragma unroll
;     for (int kt = 0; kt < 2; ++kt) {
;       f32x16 Sx[2];
;       f32x16 zero16;
; #pragma unroll
;       for (int i = 0; i < 16; ++i) zero16[i] = 0.f;
; #pragma unroll
;       for (int ks = 0; ks < 4; ++ks) {
;         const bf16x8 kf = *(const bf16x8*)(k_ + (32 * kt + r) * 72 + 16 * ks + 8 * hh);
; #pragma unroll
;         for (int g = 0; g < 2; ++g) Sx[g] = mfma32(kf, Qf[g][ks], ks == 0 ? zero16 : Sx[g]);
;       }
;       bf16x8 vf[2][2];
; #pragma unroll
;       for (int s = 0; s < 2; ++s)
; #pragma unroll
;         for (int dt = 0; dt < 2; ++dt) {
;           const bf16_t* vb_ = v_ + (32 * kt + 16 * s) * 72 + 32 * dt + troff;
;           const s16x4 lo = __builtin_amdgcn_ds_read_tr16_b64_v4i16((LAS s16x4*)(vb_));
;           const s16x4 hi = __builtin_amdgcn_ds_read_tr16_b64_v4i16((LAS s16x4*)(vb_ + 8 * 72));
;           vf[s][dt] = __builtin_shufflevector(lo, hi, 0, 1, 2, 3, 4, 5, 6, 7);
;         }
; #pragma unroll
;       for (int g = 0; g < 2; ++g) {
;         float pv[16];
; #pragma unroll
;         for (int i = 0; i < 16; ++i) { pv[i] = __builtin_amdgcn_exp2f(Sx[g][i]); lsum[g] += pv[i]; }
;         bf16x8 Pb[2];
; #pragma unroll
;         for (int s = 0; s < 2; ++s) {
;           const u32x4 w = {pk2(pv[8 * s], pv[8 * s + 1]), pk2(pv[8 * s + 2], pv[8 * s + 3]), pk2(pv[8 * s + 4], pv[8 * s + 5]), pk2(pv[8 * s + 6], pv[8 * s + 7])};
;           Pb[s] = __builtin_bit_cast(bf16x8, w);
;         }
; #pragma unroll
;         for (int s = 0; s < 2; ++s)
; #pragma unroll
;           for (int dt = 0; dt < 2; ++dt) O[dt][g] = mfma32(vf[s][dt], Pb[s], O[dt][g]);
;       }
;     }
.LBB0_99:
	s_add_i32 s5, s4, 64
	global_load_dwordx4 v[128:131], v[238:239], off
	global_load_dwordx4 v[132:135], v[238:239], off offset:256
	global_load_dwordx4 v[136:139], v[240:241], off
	global_load_dwordx4 v[140:143], v[240:241], off offset:256
	v_lshl_add_u64 v[238:239], v[238:239], 0, s[6:7]
	v_lshl_add_u64 v[240:241], v[240:241], 0, s[6:7]
	s_and_b32 s2, s4, 64
	s_mulk_i32 s2, 0x90
	v_add_u32_e32 v205, s2, v160
	ds_read_b128 v[64:67], v205
	ds_read_b128 v[144:147], v205 offset:32
	v_add_u32_e32 v153, s2, v165
	s_and_b32 s2, s5, 64
	s_mulk_i32 s2, 0x90
	s_waitcnt lgkmcnt(1)
	v_mfma_f32_32x32x16_bf16 v[80:95], v[64:67], v[116:119], 0
	s_cmpk_eq_i32 s5, 0xfc0
	s_mov_b32 s4, s5
	v_mfma_f32_32x32x16_bf16 v[64:79], v[64:67], v[124:127], 0
	s_waitcnt lgkmcnt(0)
	v_mfma_f32_32x32x16_bf16 v[80:95], v[144:147], v[108:111], v[80:95]
	v_mfma_f32_32x32x16_bf16 v[64:79], v[144:147], v[120:123], v[64:79]
	ds_read_b128 v[144:147], v205 offset:64
	s_waitcnt lgkmcnt(0)
	v_mfma_f32_32x32x16_bf16 v[80:95], v[144:147], v[100:103], v[80:95]
	v_mfma_f32_32x32x16_bf16 v[64:79], v[144:147], v[112:115], v[64:79]
	ds_read_b128 v[144:147], v205 offset:96
	s_waitcnt lgkmcnt(0)
	v_mfma_f32_32x32x16_bf16 v[80:95], v[144:147], v[96:99], v[80:95]
	v_mfma_f32_32x32x16_bf16 v[64:79], v[144:147], v[104:107], v[64:79]
	ds_read_b64_tr_b16 v[206:207], v153 offset:18432
	ds_read_b64_tr_b16 v[208:209], v153 offset:19584
	ds_read_b64_tr_b16 v[210:211], v153 offset:18496
	ds_read_b64_tr_b16 v[212:213], v153 offset:19648
	ds_read_b64_tr_b16 v[144:145], v153 offset:20736
	ds_read_b64_tr_b16 v[146:147], v153 offset:21888
	ds_read_b64_tr_b16 v[148:149], v153 offset:20800
	ds_read_b64_tr_b16 v[150:151], v153 offset:21952
	s_nop 2
	v_exp_f32_e32 v157, v80
	v_exp_f32_e32 v81, v81
	v_exp_f32_e32 v215, v82
	v_exp_f32_e32 v83, v83
	v_exp_f32_e32 v217, v84
	v_exp_f32_e32 v85, v85
	v_exp_f32_e32 v219, v86
	v_exp_f32_e32 v87, v87
	v_exp_f32_e32 v156, v64
	v_exp_f32_e32 v80, v65
	v_exp_f32_e32 v214, v66
	v_exp_f32_e32 v82, v67
	v_cvt_pk_bf16_f32 v64, v157, v81
	v_cvt_pk_bf16_f32 v65, v215, v83
	v_cvt_pk_bf16_f32 v66, v217, v85
	v_cvt_pk_bf16_f32 v67, v219, v87
	v_exp_f32_e32 v216, v68
	v_exp_f32_e32 v84, v69
	s_waitcnt lgkmcnt(6)
	v_mfma_f32_32x32x16_bf16 v[48:63], v[206:209], v[64:67], v[48:63]
	v_exp_f32_e32 v218, v70
	v_exp_f32_e32 v86, v71
	v_exp_f32_e32 v221, v88
	v_exp_f32_e32 v220, v72
	v_exp_f32_e32 v89, v89
	v_exp_f32_e32 v88, v73
	v_exp_f32_e32 v159, v90
	s_waitcnt lgkmcnt(4)
	v_mfma_f32_32x32x16_bf16 v[32:47], v[210:213], v[64:67], v[32:47]
	v_add_f32_e64 v64, v154, v156
	v_add_f32_e64 v65, v155, v157
	v_cvt_pk_bf16_f32 v66, v216, v84
	v_add_f32_e64 v64, v80, v64
	v_add_f32_e64 v65, v81, v65
	v_cvt_pk_bf16_f32 v67, v218, v86
	v_add_f32_e32 v64, v214, v64
	v_add_f32_e32 v65, v215, v65
	v_exp_f32_e32 v171, v91
	v_add_f32_e32 v64, v82, v64
	v_add_f32_e32 v65, v83, v65
	v_exp_f32_e32 v169, v92
	v_add_f32_e32 v64, v216, v64
	v_add_f32_e32 v65, v217, v65
	v_exp_f32_e32 v175, v93
	v_add_f32_e32 v64, v84, v64
	v_add_f32_e32 v65, v85, v65
	v_exp_f32_e32 v173, v94
	v_add_f32_e32 v64, v218, v64
	v_add_f32_e32 v65, v219, v65
	v_exp_f32_e32 v177, v95
	v_add_f32_e32 v64, v86, v64
	v_add_f32_e32 v65, v87, v65
	v_cvt_pk_bf16_f32 v152, v221, v89
	v_add_f32_e32 v64, v220, v64
	v_add_f32_e32 v65, v221, v65
	v_exp_f32_e32 v158, v74
	v_add_f32_e32 v178, v88, v64
	v_add_f32_e32 v179, v89, v65
	v_cvt_pk_bf16_f32 v64, v156, v80
	v_cvt_pk_bf16_f32 v65, v214, v82
	v_exp_f32_e32 v170, v75
	v_exp_f32_e32 v168, v76
	v_mfma_f32_32x32x16_bf16 v[16:31], v[206:209], v[64:67], v[16:31]
	ds_read_b128 v[206:209], v205 offset:4640
	v_exp_f32_e32 v174, v77
	v_exp_f32_e32 v172, v78
	v_exp_f32_e32 v176, v79
	v_cvt_pk_bf16_f32 v156, v220, v88
	v_cvt_pk_bf16_f32 v154, v169, v175
	v_cvt_pk_bf16_f32 v155, v173, v177
	v_mfma_f32_32x32x16_bf16 v[0:15], v[210:213], v[64:67], v[0:15]
	ds_read_b128 v[64:67], v205 offset:4608
	v_cvt_pk_bf16_f32 v157, v158, v170
	s_waitcnt lgkmcnt(0)
	v_mfma_f32_32x32x16_bf16 v[80:95], v[64:67], v[116:119], 0
	v_mfma_f32_32x32x16_bf16 v[64:79], v[64:67], v[124:127], 0
	v_mfma_f32_32x32x16_bf16 v[80:95], v[206:209], v[108:111], v[80:95]
	v_mfma_f32_32x32x16_bf16 v[64:79], v[206:209], v[120:123], v[64:79]
	ds_read_b128 v[206:209], v205 offset:4672
	s_waitcnt lgkmcnt(0)
	v_mfma_f32_32x32x16_bf16 v[80:95], v[206:209], v[100:103], v[80:95]
	v_mfma_f32_32x32x16_bf16 v[64:79], v[206:209], v[112:115], v[64:79]
	ds_read_b128 v[206:209], v205 offset:4704
	s_waitcnt lgkmcnt(0)
; #define LAS __attribute__((address_space(3)))
; DI unsigned pk2(float lo, float hi) { f32x2 v = {lo, hi}; bfv2 b = __builtin_convertvector(v, bfv2); return __builtin_bit_cast(unsigned, b); }
; DI f32x16 mfma32(bf16x8 a, bf16x8 b, f32x16 c) { return __builtin_amdgcn_mfma_f32_32x32x16_bf16(a, b, c, 0, 0, 0); }
; #define AT_STORE(buf_) do { _Pragma("unroll") for (int i_ = 0; i_ < 2; ++i_) { *(u32x4*)(Ks + (buf_) * 64 * 72 + (skey + 32 * i_) * 72 + sdc) = rk[i_]; \
;     *(u32x4*)(Vs + (buf_) * 64 * 72 + (skey + 32 * i_) * 72 + sdc) = rv[i_]; } } while (0)
; DI void attn_unit(const Params& p, int unit, unsigned char* lds) {
;     ...
;       for (int ks = 0; ks < 4; ++ks) {
;         const bf16x8 kf = *(const bf16x8*)(k_ + (32 * kt + r) * 72 + 16 * ks + 8 * hh);
; #pragma unroll
;         for (int g = 0; g < 2; ++g) Sx[g] = mfma32(kf, Qf[g][ks], ks == 0 ? zero16 : Sx[g]);
;       }
;       bf16x8 vf[2][2];
; #pragma unroll
;       for (int s = 0; s < 2; ++s)
; #pragma unroll
;         for (int dt = 0; dt < 2; ++dt) {
;           const bf16_t* vb_ = v_ + (32 * kt + 16 * s) * 72 + 32 * dt + troff;
;           const s16x4 lo = __builtin_amdgcn_ds_read_tr16_b64_v4i16((LAS s16x4*)(vb_));
;           const s16x4 hi = __builtin_amdgcn_ds_read_tr16_b64_v4i16((LAS s16x4*)(vb_ + 8 * 72));
;           vf[s][dt] = __builtin_shufflevector(lo, hi, 0, 1, 2, 3, 4, 5, 6, 7);
;         }
; #pragma unroll
;       for (int g = 0; g < 2; ++g) {
;         float pv[16];
; #pragma unroll
;         for (int i = 0; i < 16; ++i) { pv[i] = __builtin_amdgcn_exp2f(Sx[g][i]); lsum[g] += pv[i]; }
;         bf16x8 Pb[2];
; #pragma unroll
;         for (int s = 0; s < 2; ++s) {
;           const u32x4 w = {pk2(pv[8 * s], pv[8 * s + 1]), pk2(pv[8 * s + 2], pv[8 * s + 3]), pk2(pv[8 * s + 4], pv[8 * s + 5]), pk2(pv[8 * s + 6], pv[8 * s + 7])};
;           Pb[s] = __builtin_bit_cast(bf16x8, w);
;         }
; #pragma unroll
;         for (int s = 0; s < 2; ++s)
; #pragma unroll
;           for (int dt = 0; dt < 2; ++dt) O[dt][g] = mfma32(vf[s][dt], Pb[s], O[dt][g]);
;       }
;     }
;     if (tl + 1 < 64) AT_STORE((tl + 1) & 1);
;     __syncthreads();
	v_mfma_f32_32x32x16_bf16 v[80:95], v[206:209], v[96:99], v[80:95]
	v_mfma_f32_32x32x16_bf16 v[64:79], v[206:209], v[104:107], v[64:79]
	ds_read_b64_tr_b16 v[206:207], v153 offset:23040
	ds_read_b64_tr_b16 v[208:209], v153 offset:24192
	ds_read_b64_tr_b16 v[210:211], v153 offset:23104
	ds_read_b64_tr_b16 v[212:213], v153 offset:24256
	ds_read_b64_tr_b16 v[214:215], v153 offset:25344
	ds_read_b64_tr_b16 v[216:217], v153 offset:26496
	ds_read_b64_tr_b16 v[218:219], v153 offset:25408
	ds_read_b64_tr_b16 v[220:221], v153 offset:26560
	s_nop 2
	v_exp_f32_e32 v223, v80
	v_exp_f32_e32 v81, v81
	v_exp_f32_e32 v225, v82
	v_cvt_pk_bf16_f32 v153, v159, v171
	v_exp_f32_e32 v83, v83
	v_exp_f32_e32 v227, v84
	v_exp_f32_e32 v222, v64
	v_exp_f32_e32 v80, v65
	v_add_f32_e32 v64, v158, v178
	v_add_f32_e32 v65, v159, v179
	v_exp_f32_e32 v224, v66
	v_add_f32_e32 v64, v170, v64
	v_add_f32_e32 v65, v171, v65
	v_exp_f32_e32 v82, v67
	v_add_f32_e32 v64, v168, v64
	v_add_f32_e32 v65, v169, v65
	v_mfma_f32_32x32x16_bf16 v[48:63], v[144:147], v[152:155], v[48:63]
	v_add_f32_e64 v64, v174, v64
	v_add_f32_e64 v65, v175, v65
	v_cvt_pk_bf16_f32 v158, v168, v174
	v_add_f32_e64 v64, v172, v64
	v_add_f32_e64 v65, v173, v65
	v_cvt_pk_bf16_f32 v159, v172, v176
	v_exp_f32_e32 v226, v68
	v_exp_f32_e32 v85, v85
	v_exp_f32_e32 v84, v69
	v_mfma_f32_32x32x16_bf16 v[32:47], v[148:151], v[152:155], v[32:47]
	v_add_f32_e64 v152, v176, v64
	v_add_f32_e64 v153, v177, v65
	v_exp_f32_e32 v229, v86
	v_exp_f32_e32 v87, v87
	v_exp_f32_e32 v228, v70
	v_exp_f32_e32 v86, v71
	v_exp_f32_e32 v231, v88
	v_exp_f32_e32 v230, v72
	v_mfma_f32_32x32x16_bf16 v[16:31], v[144:147], v[156:159], v[16:31]
	v_add_f32_e64 v144, v152, v222
	v_add_f32_e64 v145, v153, v223
	v_exp_f32_e32 v89, v89
	v_add_f32_e32 v144, v80, v144
	v_add_f32_e32 v145, v81, v145
	v_exp_f32_e32 v88, v73
	v_add_f32_e32 v144, v224, v144
	v_add_f32_e32 v145, v225, v145
	v_exp_f32_e32 v233, v90
	v_add_f32_e32 v144, v82, v144
	v_add_f32_e32 v145, v83, v145
	v_mfma_f32_32x32x16_bf16 v[0:15], v[148:151], v[156:159], v[0:15]
	v_add_f32_e64 v144, v226, v144
	v_add_f32_e64 v145, v227, v145
	v_cvt_pk_bf16_f32 v64, v223, v81
	v_add_f32_e64 v68, v84, v144
	v_add_f32_e64 v69, v85, v145
	v_cvt_pk_bf16_f32 v65, v225, v83
	v_cvt_pk_bf16_f32 v66, v227, v85
	v_exp_f32_e32 v232, v74
	v_add_f32_e32 v68, v228, v68
	v_add_f32_e32 v69, v229, v69
	v_cvt_pk_bf16_f32 v67, v229, v87
	v_exp_f32_e32 v91, v91
	v_exp_f32_e32 v90, v75
	v_add_f32_e32 v68, v86, v68
	v_add_f32_e32 v69, v87, v69
	s_waitcnt lgkmcnt(6)
	v_mfma_f32_32x32x16_bf16 v[48:63], v[206:209], v[64:67], v[48:63]
	v_exp_f32_e32 v235, v92
	v_exp_f32_e32 v234, v76
	v_add_f32_e32 v68, v230, v68
	v_add_f32_e32 v69, v231, v69
	v_exp_f32_e32 v93, v93
	v_exp_f32_e32 v92, v77
	v_add_f32_e32 v68, v88, v68
	v_add_f32_e32 v69, v89, v69
	v_exp_f32_e32 v237, v94
	s_waitcnt lgkmcnt(4)
	v_mfma_f32_32x32x16_bf16 v[32:47], v[210:213], v[64:67], v[32:47]
	v_cvt_pk_bf16_f32 v64, v222, v80
	v_cvt_pk_bf16_f32 v65, v224, v82
	v_cvt_pk_bf16_f32 v66, v226, v84
	v_cvt_pk_bf16_f32 v67, v228, v86
	v_exp_f32_e32 v95, v95
	v_exp_f32_e32 v236, v78
	v_add_f32_e32 v68, v232, v68
	v_add_f32_e32 v69, v233, v69
	v_mfma_f32_32x32x16_bf16 v[16:31], v[206:209], v[64:67], v[16:31]
	v_exp_f32_e32 v94, v79
	v_add_f32_e32 v68, v90, v68
	v_add_f32_e32 v69, v91, v69
	v_cvt_pk_bf16_f32 v70, v235, v93
	v_add_f32_e32 v68, v234, v68
	v_add_f32_e32 v69, v235, v69
	v_cvt_pk_bf16_f32 v71, v237, v95
	v_add_f32_e32 v68, v92, v68
	v_add_f32_e32 v69, v93, v69
	v_mfma_f32_32x32x16_bf16 v[0:15], v[210:213], v[64:67], v[0:15]
	v_add_f32_e64 v72, v236, v68
	v_add_f32_e64 v73, v237, v69
	v_cvt_pk_bf16_f32 v68, v231, v89
	v_cvt_pk_bf16_f32 v69, v233, v91
	v_add_f32_e64 v154, v94, v72
	v_add_f32_e64 v155, v95, v73
	v_add_u32_e32 v64, s2, v204
	s_waitcnt vmcnt(3)
	ds_write_b128 v64, v[128:131]
	s_waitcnt vmcnt(2)
	ds_write_b128 v64, v[132:135] offset:18432
	s_waitcnt vmcnt(1)
	ds_write_b128 v64, v[136:139] offset:4608
	s_waitcnt vmcnt(0)
	ds_write_b128 v64, v[140:143] offset:23040
	s_waitcnt lgkmcnt(0)
	v_mfma_f32_32x32x16_bf16 v[48:63], v[214:217], v[68:71], v[48:63]
	s_barrier
	v_mfma_f32_32x32x16_bf16 v[32:47], v[218:221], v[68:71], v[32:47]
	v_cvt_pk_bf16_f32 v68, v230, v88
	v_cvt_pk_bf16_f32 v69, v232, v90
	v_cvt_pk_bf16_f32 v70, v234, v92
	v_cvt_pk_bf16_f32 v71, v236, v94
	s_nop 1
	v_mfma_f32_32x32x16_bf16 v[16:31], v[214:217], v[68:71], v[16:31]
	v_mfma_f32_32x32x16_bf16 v[0:15], v[218:221], v[68:71], v[0:15]
	s_cbranch_scc0 .LBB0_99
; #define LAS __attribute__((address_space(3)))
; DI unsigned pk2(float lo, float hi) { f32x2 v = {lo, hi}; bfv2 b = __builtin_convertvector(v, bfv2); return __builtin_bit_cast(unsigned, b); }
; DI f32x16 mfma32(bf16x8 a, bf16x8 b, f32x16 c) { return __builtin_amdgcn_mfma_f32_32x32x16_bf16(a, b, c, 0, 0, 0); }
; DI void attn_unit(const Params& p, int unit, unsigned char* lds) {
;     ...
;     const bf16_t* k_ = Ks + (tl & 1) * 64 * 72; const bf16_t* v_ = Vs + (tl & 1) * 64 * 72;
; #pragma unroll
;     for (int kt = 0; kt < 2; ++kt) {
;       f32x16 Sx[2];
;       f32x16 zero16;
; #pragma unroll
;       for (int i = 0; i < 16; ++i) zero16[i] = 0.f;
; #pragma unroll
;       for (int ks = 0; ks < 4; ++ks) {
;         const bf16x8 kf = *(const bf16x8*)(k_ + (32 * kt + r) * 72 + 16 * ks + 8 * hh);
; #pragma unroll
;         for (int g = 0; g < 2; ++g) Sx[g] = mfma32(kf, Qf[g][ks], ks == 0 ? zero16 : Sx[g]);
;       }
;       bf16x8 vf[2][2];
; #pragma unroll
;       for (int s = 0; s < 2; ++s)
; #pragma unroll
;         for (int dt = 0; dt < 2; ++dt) {
;           const bf16_t* vb_ = v_ + (32 * kt + 16 * s) * 72 + 32 * dt + troff;
;           const s16x4 lo = __builtin_amdgcn_ds_read_tr16_b64_v4i16((LAS s16x4*)(vb_));
;           const s16x4 hi = __builtin_amdgcn_ds_read_tr16_b64_v4i16((LAS s16x4*)(vb_ + 8 * 72));
;           vf[s][dt] = __builtin_shufflevector(lo, hi, 0, 1, 2, 3, 4, 5, 6, 7);
;         }
; #pragma unroll
;       for (int g = 0; g < 2; ++g) {
;         float pv[16];
; #pragma unroll
;         for (int i = 0; i < 16; ++i) { pv[i] = __builtin_amdgcn_exp2f(Sx[g][i]); lsum[g] += pv[i]; }
;         bf16x8 Pb[2];
; #pragma unroll
;         for (int s = 0; s < 2; ++s) {
;           const u32x4 w = {pk2(pv[8 * s], pv[8 * s + 1]), pk2(pv[8 * s + 2], pv[8 * s + 3]), pk2(pv[8 * s + 4], pv[8 * s + 5]), pk2(pv[8 * s + 6], pv[8 * s + 7])};
;           Pb[s] = __builtin_bit_cast(bf16x8, w);
;         }
; #pragma unroll
;         for (int s = 0; s < 2; ++s)
; #pragma unroll
;           for (int dt = 0; dt < 2; ++dt) O[dt][g] = mfma32(vf[s][dt], Pb[s], O[dt][g]);
;       }
;     }
;     if (tl + 1 < 64) AT_STORE((tl + 1) & 1);
;     __syncthreads();
;   }
;     ...
;   const int pcol = kvc == 0 ? A_V : (kvc == 1 ? A_Z : (kvc == 2 ? B_V : D_X));
	ds_read_b128 v[64:67], v160 offset:9216
	ds_read_b128 v[128:131], v160 offset:9248
	s_cmp_lt_i32 s34, 1
	s_mov_b64 s[8:9], 0x100
	s_waitcnt lgkmcnt(1)
	v_mfma_f32_32x32x16_bf16 v[80:95], v[64:67], v[116:119], 0
	v_mfma_f32_32x32x16_bf16 v[64:79], v[64:67], v[124:127], 0
	s_waitcnt lgkmcnt(0)
	v_mfma_f32_32x32x16_bf16 v[80:95], v[128:131], v[108:111], v[80:95]
	v_mfma_f32_32x32x16_bf16 v[64:79], v[128:131], v[120:123], v[64:79]
	ds_read_b128 v[128:131], v160 offset:9280
	s_waitcnt lgkmcnt(0)
	v_mfma_f32_32x32x16_bf16 v[80:95], v[128:131], v[100:103], v[80:95]
	v_mfma_f32_32x32x16_bf16 v[64:79], v[128:131], v[112:115], v[64:79]
	ds_read_b128 v[128:131], v160 offset:9312
	ds_read_b64_tr_b16 v[168:169], v165 offset:27648
	ds_read_b64_tr_b16 v[170:171], v165 offset:28800
	ds_read_b64_tr_b16 v[172:173], v165 offset:27712
	ds_read_b64_tr_b16 v[174:175], v165 offset:28864
	ds_read_b64_tr_b16 v[176:177], v165 offset:29952
	ds_read_b64_tr_b16 v[178:179], v165 offset:31104
	ds_read_b64_tr_b16 v[204:205], v165 offset:30016
	ds_read_b64_tr_b16 v[206:207], v165 offset:31168
	s_waitcnt lgkmcnt(8)
	v_mfma_f32_32x32x16_bf16 v[64:79], v[128:131], v[104:107], v[64:79]
	v_mfma_f32_32x32x16_bf16 v[80:95], v[128:131], v[96:99], v[80:95]
	s_nop 10
	v_exp_f32_e32 v128, v64
	v_exp_f32_e32 v129, v65
	v_exp_f32_e32 v130, v66
	v_exp_f32_e32 v131, v67
	v_exp_f32_e32 v132, v68
	v_exp_f32_e32 v133, v69
	v_exp_f32_e32 v134, v70
	v_exp_f32_e32 v135, v71
	v_exp_f32_e32 v144, v80
	v_exp_f32_e32 v145, v81
	v_exp_f32_e32 v146, v82
	v_exp_f32_e32 v147, v83
	v_exp_f32_e32 v148, v84
	v_exp_f32_e32 v149, v85
	v_exp_f32_e32 v150, v86
	v_exp_f32_e32 v151, v87
	v_cvt_pk_bf16_f32 v64, v128, v129
	v_cvt_pk_bf16_f32 v65, v130, v131
	v_cvt_pk_bf16_f32 v66, v132, v133
	v_cvt_pk_bf16_f32 v67, v134, v135
	v_cvt_pk_bf16_f32 v80, v144, v145
	v_cvt_pk_bf16_f32 v81, v146, v147
	v_cvt_pk_bf16_f32 v82, v148, v149
	v_cvt_pk_bf16_f32 v83, v150, v151
	s_waitcnt lgkmcnt(6)
	v_mfma_f32_32x32x16_bf16 v[16:31], v[168:171], v[64:67], v[16:31]
	v_exp_f32_e32 v152, v88
	v_exp_f32_e32 v153, v89
	v_exp_f32_e32 v156, v90
	v_exp_f32_e32 v157, v91
	v_exp_f32_e32 v158, v92
	v_exp_f32_e32 v159, v93
	v_exp_f32_e32 v166, v94
	s_waitcnt lgkmcnt(4)
	v_mfma_f32_32x32x16_bf16 v[0:15], v[172:175], v[64:67], v[0:15]
	ds_read_b128 v[64:67], v160 offset:13824
	v_exp_f32_e32 v167, v95
	v_cvt_pk_bf16_f32 v84, v152, v153
	v_cvt_pk_bf16_f32 v85, v156, v157
	v_cvt_pk_bf16_f32 v86, v158, v159
	v_cvt_pk_bf16_f32 v87, v166, v167
	v_exp_f32_e32 v136, v72
	v_mfma_f32_32x32x16_bf16 v[48:63], v[168:171], v[80:83], v[48:63]
	v_exp_f32_e32 v137, v73
	v_exp_f32_e32 v138, v74
	v_exp_f32_e32 v139, v75
	v_exp_f32_e32 v140, v76
	v_exp_f32_e32 v141, v77
	v_exp_f32_e32 v142, v78
	v_exp_f32_e32 v143, v79
	v_mfma_f32_32x32x16_bf16 v[32:47], v[172:175], v[80:83], v[32:47]
	v_cvt_pk_bf16_f32 v68, v136, v137
	v_cvt_pk_bf16_f32 v69, v138, v139
	v_cvt_pk_bf16_f32 v70, v140, v141
	v_cvt_pk_bf16_f32 v71, v142, v143
	s_waitcnt lgkmcnt(3)
	v_mfma_f32_32x32x16_bf16 v[48:63], v[176:179], v[84:87], v[48:63]
	s_waitcnt lgkmcnt(1)
	v_mfma_f32_32x32x16_bf16 v[32:47], v[204:207], v[84:87], v[32:47]
	s_waitcnt lgkmcnt(0)
	v_mfma_f32_32x32x16_bf16 v[80:95], v[64:67], v[116:119], 0
	ds_read_b128 v[116:119], v160 offset:13856
	v_mfma_f32_32x32x16_bf16 v[16:31], v[176:179], v[68:71], v[16:31]
	v_mfma_f32_32x32x16_bf16 v[0:15], v[204:207], v[68:71], v[0:15]
	v_mfma_f32_32x32x16_bf16 v[64:79], v[64:67], v[124:127], 0
	s_waitcnt lgkmcnt(0)
	v_mfma_f32_32x32x16_bf16 v[80:95], v[116:119], v[108:111], v[80:95]
	ds_read_b128 v[108:111], v160 offset:13888
	v_mfma_f32_32x32x16_bf16 v[64:79], v[116:119], v[120:123], v[64:79]
	s_waitcnt lgkmcnt(0)
	v_mfma_f32_32x32x16_bf16 v[80:95], v[108:111], v[100:103], v[80:95]
	ds_read_b128 v[100:103], v160 offset:13920
	v_mfma_f32_32x32x16_bf16 v[64:79], v[108:111], v[112:115], v[64:79]
	s_waitcnt lgkmcnt(0)
	v_mfma_f32_32x32x16_bf16 v[80:95], v[100:103], v[96:99], v[80:95]
	v_mfma_f32_32x32x16_bf16 v[64:79], v[100:103], v[104:107], v[64:79]
	s_nop 10
	v_exp_f32_e32 v80, v80
	v_exp_f32_e32 v81, v81
	v_exp_f32_e32 v82, v82
	v_exp_f32_e32 v83, v83
	v_exp_f32_e32 v84, v84
	v_exp_f32_e32 v85, v85
	v_exp_f32_e32 v86, v86
	v_exp_f32_e32 v87, v87
	ds_read_b64_tr_b16 v[108:109], v165 offset:32256
	ds_read_b64_tr_b16 v[110:111], v165 offset:33408
	ds_read_b64_tr_b16 v[104:105], v165 offset:32320
	ds_read_b64_tr_b16 v[106:107], v165 offset:33472
	ds_read_b64_tr_b16 v[96:97], v165 offset:34560
	ds_read_b64_tr_b16 v[98:99], v165 offset:35712
	ds_read_b64_tr_b16 v[100:101], v165 offset:34624
	ds_read_b64_tr_b16 v[102:103], v165 offset:35776
	v_cvt_pk_bf16_f32 v112, v80, v81
	v_cvt_pk_bf16_f32 v113, v82, v83
	v_cvt_pk_bf16_f32 v114, v84, v85
	v_cvt_pk_bf16_f32 v115, v86, v87
	v_exp_f32_e32 v68, v68
	v_exp_f32_e32 v69, v69
	s_waitcnt lgkmcnt(6)
	v_mfma_f32_32x32x16_bf16 v[48:63], v[108:111], v[112:115], v[48:63]
	v_exp_f32_e32 v70, v70
	v_exp_f32_e32 v71, v71
	v_exp_f32_e32 v88, v88
	v_exp_f32_e32 v89, v89
	v_exp_f32_e32 v90, v90
	v_exp_f32_e32 v91, v91
	v_exp_f32_e32 v92, v92
	s_waitcnt lgkmcnt(4)
	v_mfma_f32_32x32x16_bf16 v[32:47], v[104:107], v[112:115], v[32:47]
	v_exp_f32_e32 v112, v64
	v_exp_f32_e32 v113, v65
	v_exp_f32_e32 v114, v66
	v_exp_f32_e32 v115, v67
	v_cvt_pk_bf16_f32 v66, v68, v69
	v_cvt_pk_bf16_f32 v64, v112, v113
	v_cvt_pk_bf16_f32 v67, v70, v71
	v_cvt_pk_bf16_f32 v65, v114, v115
	v_exp_f32_e32 v93, v93
	v_exp_f32_e32 v94, v94
	v_mfma_f32_32x32x16_bf16 v[16:31], v[108:111], v[64:67], v[16:31]
	v_exp_f32_e32 v95, v95
	v_exp_f32_e32 v72, v72
	v_exp_f32_e32 v73, v73
	v_exp_f32_e32 v74, v74
	v_exp_f32_e32 v75, v75
	v_exp_f32_e32 v76, v76
	v_exp_f32_e32 v77, v77
	v_mfma_f32_32x32x16_bf16 v[0:15], v[104:107], v[64:67], v[0:15]
	v_exp_f32_e32 v78, v78
	v_exp_f32_e32 v79, v79
	v_cvt_pk_bf16_f32 v116, v88, v89
	v_cvt_pk_bf16_f32 v117, v90, v91
	v_cvt_pk_bf16_f32 v118, v92, v93
	v_cvt_pk_bf16_f32 v119, v94, v95
	s_waitcnt lgkmcnt(0)
	s_barrier
	v_mfma_f32_32x32x16_bf16 v[48:63], v[96:99], v[116:119], v[48:63]
	v_mfma_f32_32x32x16_bf16 v[32:47], v[100:103], v[116:119], v[32:47]
	v_cvt_pk_bf16_f32 v116, v72, v73
	v_cvt_pk_bf16_f32 v117, v74, v75
	v_cvt_pk_bf16_f32 v118, v76, v77
	v_cvt_pk_bf16_f32 v119, v78, v79
	s_nop 1
	v_mfma_f32_32x32x16_bf16 v[16:31], v[96:99], v[116:119], v[16:31]
	v_mfma_f32_32x32x16_bf16 v[0:15], v[100:103], v[116:119], v[0:15]
	s_cbranch_scc1 .LBB0_105
	s_cmp_lg_u32 s34, 1
	s_mov_b64 s[4:5], -1
	s_cbranch_scc0 .LBB0_103
	s_cmp_eq_u32 s34, 2
	s_cselect_b32 s84, s45, 0xa00
	s_mov_b64 s[4:5], 0
	s_mov_b64 s[8:9], s[84:85]
